# v9 + K-fragment LDS prefetch depth 4 in fused attention QK
# speedup vs baseline: 1.0065x; 1.0065x over previous
.LBB0_742:
	s_add_i32 s27, s63, -3
	s_add_u32 s24, s76, s18
	s_addc_u32 s28, s77, s19
	s_add_u32 s10, s24, 0xe212000
	s_addc_u32 s11, s28, 0
	s_mul_i32 s25, s16, 0x6000
	v_lshl_add_u64 v[200:201], v[180:181], 1, s[10:11]
	s_add_i32 s12, s25, s49
	s_mov_b32 s13, m0
	s_mov_b32 m0, s12
	s_nop 0
	global_load_lds_dwordx4 v[200:201], off
	s_mov_b32 m0, s13
	v_lshl_add_u64 v[200:201], v[182:183], 1, s[10:11]
	s_mov_b32 s26, s16
	s_add_i32 s13, s12, 0x2000
	s_mov_b32 s16, m0
	s_mov_b32 m0, s13
	s_nop 0
	global_load_lds_dwordx4 v[200:201], off
	s_mov_b32 m0, s16
	v_lshl_add_u64 v[200:201], v[184:185], 1, s[10:11]
	s_add_i32 s10, s12, 0x4000
	s_add_u32 s29, s76, s20
	s_addc_u32 s30, s77, s21
	s_mov_b32 s11, m0
	s_mov_b32 m0, s10
	s_nop 0
	global_load_lds_dwordx4 v[200:201], off
	s_mov_b32 m0, s11
	s_add_u32 s10, s29, 0x14208000
	s_addc_u32 s11, s30, 0
	s_lshl_b32 s22, s4, 14
	s_add_i32 s12, s22, s51
	v_lshl_add_u64 v[200:201], v[186:187], 1, s[10:11]
	s_mov_b32 s13, m0
	s_mov_b32 m0, s12
	s_nop 0
	global_load_lds_dwordx4 v[200:201], off
	s_mov_b32 m0, s13
	v_lshl_add_u64 v[200:201], v[188:189], 1, s[10:11]
	s_add_i32 s10, s12, 0x2000
	s_mov_b32 s11, m0
	s_mov_b32 m0, s10
	s_nop 0
	global_load_lds_dwordx4 v[200:201], off
	s_mov_b32 m0, s11
	s_cmp_le_i32 s27, s52
	s_cselect_b64 s[12:13], -1, 0
	s_and_b64 vcc, exec, s[12:13]
	s_mul_i32 s31, s62, 0x6000
	s_cbranch_vccz .LBB0_745
	v_add_u32_e32 v232, s31, v206
	v_add_u32_e32 v233, s31, v207
	v_add_u32_e32 v234, s31, v208
	v_add_u32_e32 v235, s31, v209
	ds_read_b128 v[64:67], v232 offset:0
	ds_read_b128 v[68:71], v232 offset:12288
	ds_read_b128 v[200:203], v233 offset:0
	ds_read_b128 v[212:215], v233 offset:12288
	ds_read_b128 v[216:219], v234 offset:0
	ds_read_b128 v[220:223], v234 offset:12288
	ds_read_b128 v[224:227], v235 offset:0
	ds_read_b128 v[228:231], v235 offset:12288
	ds_read_b128 v[244:247], v232 offset:128
	ds_read_b128 v[248:251], v232 offset:12416
	s_waitcnt lgkmcnt(8)
	v_mfma_f32_32x32x16_bf16 v[80:95], v[64:67], v[172:175], 0
	v_add_f32_e32 v241, 0, v112
	v_add_f32_e32 v241, v113, v241
	v_add_f32_e32 v241, v114, v241
	v_add_f32_e32 v241, v115, v241
	v_mfma_f32_32x32x16_bf16 v[64:79], v[68:71], v[172:175], 0
	v_add_f32_e32 v241, v116, v241
	v_add_f32_e32 v241, v117, v241
	v_add_f32_e32 v241, v118, v241
	v_add_f32_e32 v241, v119, v241
	s_waitcnt lgkmcnt(6)
	v_mfma_f32_32x32x16_bf16 v[80:95], v[200:203], v[168:171], v[80:95]
	v_add_f32_e32 v241, v120, v241
	v_add_f32_e32 v241, v121, v241
	v_add_f32_e32 v241, v122, v241
	v_add_f32_e32 v241, v123, v241
	ds_read_b128 v[200:203], v233 offset:128
	v_mfma_f32_32x32x16_bf16 v[64:79], v[212:215], v[168:171], v[64:79]
	v_exp_f32_e32 v96, v96
	v_add_f32_e32 v241, v124, v241
	v_exp_f32_e32 v97, v97
	v_add_f32_e32 v241, v125, v241
	ds_read_b128 v[212:215], v233 offset:12416
	s_waitcnt lgkmcnt(6)
	v_mfma_f32_32x32x16_bf16 v[80:95], v[216:219], v[164:167], v[80:95]
	v_exp_f32_e32 v98, v98
	v_add_f32_e32 v241, v126, v241
	v_exp_f32_e32 v99, v99
	v_add_f32_e32 v241, v127, v241
	ds_read_b128 v[216:219], v234 offset:128
	v_mfma_f32_32x32x16_bf16 v[64:79], v[220:223], v[164:167], v[64:79]
	v_exp_f32_e32 v100, v100
	v_add_f32_e32 v241, v96, v241
	v_exp_f32_e32 v101, v101
	v_add_f32_e32 v241, v97, v241
	ds_read_b128 v[220:223], v234 offset:12416
	s_waitcnt lgkmcnt(6)
	v_mfma_f32_32x32x16_bf16 v[80:95], v[224:227], v[160:163], v[80:95]
	v_exp_f32_e32 v102, v102
	v_add_f32_e32 v241, v98, v241
	v_exp_f32_e32 v103, v103
	v_add_f32_e32 v241, v99, v241
	ds_read_b128 v[224:227], v235 offset:128
	v_mfma_f32_32x32x16_bf16 v[64:79], v[228:231], v[160:163], v[64:79]
	v_exp_f32_e32 v104, v104
	v_add_f32_e32 v241, v100, v241
	v_exp_f32_e32 v105, v105
	v_add_f32_e32 v241, v101, v241
	ds_read_b128 v[228:231], v235 offset:12416
	s_waitcnt lgkmcnt(6)
	v_mfma_f32_32x32x16_bf16 v[80:95], v[244:247], v[156:159], v[80:95]
	v_exp_f32_e32 v106, v106
	v_add_f32_e32 v241, v102, v241
	v_exp_f32_e32 v107, v107
	ds_read_b128 v[244:247], v232 offset:256
	v_mfma_f32_32x32x16_bf16 v[64:79], v[248:251], v[156:159], v[64:79]
	v_add_f32_e32 v241, v103, v241
	v_exp_f32_e32 v108, v108
	v_add_f32_e32 v241, v104, v241
	ds_read_b128 v[248:251], v232 offset:12544
	s_waitcnt lgkmcnt(6)
	v_mfma_f32_32x32x16_bf16 v[80:95], v[200:203], v[152:155], v[80:95]
	v_exp_f32_e32 v109, v109
	v_add_f32_e32 v241, v105, v241
	v_exp_f32_e32 v110, v110
	ds_read_b128 v[200:203], v233 offset:256
	v_mfma_f32_32x32x16_bf16 v[64:79], v[212:215], v[152:155], v[64:79]
	v_add_f32_e32 v241, v106, v241
	v_exp_f32_e32 v111, v111
	v_add_f32_e32 v241, v107, v241
	ds_read_b128 v[212:215], v233 offset:12544
	s_waitcnt lgkmcnt(6)
	v_mfma_f32_32x32x16_bf16 v[80:95], v[216:219], v[148:151], v[80:95]
	v_add_f32_e32 v241, v108, v241
	v_add_f32_e32 v241, v109, v241
	v_add_f32_e32 v241, v110, v241
	ds_read_b128 v[216:219], v234 offset:256
	v_mfma_f32_32x32x16_bf16 v[64:79], v[220:223], v[148:151], v[64:79]
	v_add_f32_e32 v241, v111, v241
	v_mov_b32_e32 v242, v241
	v_cvt_pk_bf16_f32 v112, v112, v113
	ds_read_b128 v[220:223], v234 offset:12544
	s_waitcnt lgkmcnt(6)
	v_mfma_f32_32x32x16_bf16 v[80:95], v[224:227], v[144:147], v[80:95]
	v_cvt_pk_bf16_f32 v113, v114, v115
	v_permlane32_swap_b32_e32 v241, v242
	v_cvt_pk_bf16_f32 v114, v116, v117
	ds_read_b128 v[224:227], v235 offset:256
	v_mfma_f32_32x32x16_bf16 v[64:79], v[228:231], v[144:147], v[64:79]
	v_cvt_pk_bf16_f32 v115, v118, v119
	v_cvt_pk_bf16_f32 v116, v120, v121
	v_cvt_pk_bf16_f32 v117, v122, v123
	ds_read_b128 v[228:231], v235 offset:12544
	s_waitcnt lgkmcnt(6)
	v_mfma_f32_32x32x16_bf16 v[80:95], v[244:247], v[140:143], v[80:95]
	v_cvt_pk_bf16_f32 v118, v124, v125
	v_cvt_pk_bf16_f32 v119, v126, v127
	v_cvt_pk_bf16_f32 v96, v96, v97
	v_mfma_f32_32x32x16_bf16 v[64:79], v[248:251], v[140:143], v[64:79]
	v_cvt_pk_bf16_f32 v97, v98, v99
	v_cvt_pk_bf16_f32 v98, v100, v101
	v_cvt_pk_bf16_f32 v99, v102, v103
	s_waitcnt lgkmcnt(4)
	v_mfma_f32_32x32x16_bf16 v[80:95], v[200:203], v[136:139], v[80:95]
	v_cvt_pk_bf16_f32 v100, v104, v105
	v_cvt_pk_bf16_f32 v101, v106, v107
	v_cvt_pk_bf16_f32 v102, v108, v109
	v_mfma_f32_32x32x16_bf16 v[64:79], v[212:215], v[136:139], v[64:79]
	v_cvt_pk_bf16_f32 v103, v110, v111
	v_add_f32_e32 v243, v241, v242
	v_fmac_f32_e32 v243, v210, v211
	s_waitcnt lgkmcnt(2)
	v_mfma_f32_32x32x16_bf16 v[80:95], v[216:219], v[132:135], v[80:95]
	v_permlane32_swap_b32_e32 v112, v114
	v_permlane32_swap_b32_e32 v113, v115
	v_permlane32_swap_b32_e32 v116, v118
	v_mfma_f32_32x32x16_bf16 v[64:79], v[220:223], v[132:135], v[64:79]
	v_permlane32_swap_b32_e32 v117, v119
	v_permlane32_swap_b32_e32 v96, v98
	v_permlane32_swap_b32_e32 v97, v99
	s_waitcnt lgkmcnt(0)
	v_mfma_f32_32x32x16_bf16 v[80:95], v[224:227], v[128:131], v[80:95]
	v_permlane32_swap_b32_e32 v100, v102
	v_permlane32_swap_b32_e32 v101, v103
	v_mov_b32_e32 v211, v243
	v_mfma_f32_32x32x16_bf16 v[64:79], v[228:231], v[128:131], v[64:79]
	v_lshl_add_u32 v244, s26, 14, v196
	ds_read_b64_tr_b16 v[224:225], v244 offset:0
	ds_read_b64_tr_b16 v[226:227], v244 offset:2048
	ds_read_b64_tr_b16 v[228:229], v244 offset:512
	ds_read_b64_tr_b16 v[230:231], v244 offset:2560
	ds_read_b64_tr_b16 v[232:233], v244 offset:1024
	ds_read_b64_tr_b16 v[234:235], v244 offset:3072
	ds_read_b64_tr_b16 v[236:237], v244 offset:1536
	ds_read_b64_tr_b16 v[238:239], v244 offset:3584
	s_waitcnt lgkmcnt(0)
	v_mfma_f32_32x32x16_bf16 v[32:47], v[112:115], v[224:227], v[32:47]
	v_max_f32_e32 v246, v81, v81
	v_max_f32_e32 v247, v80, v80
	v_max_f32_e32 v246, v247, v246
	v_max3_f32 v246, v246, v82, v83
	v_max3_f32 v246, v246, v84, v85
	ds_read_b64_tr_b16 v[200:201], v244 offset:4096
	ds_read_b64_tr_b16 v[202:203], v244 offset:6144
	ds_read_b64_tr_b16 v[212:213], v244 offset:4608
	ds_read_b64_tr_b16 v[214:215], v244 offset:6656
	ds_read_b64_tr_b16 v[216:217], v244 offset:5120
	ds_read_b64_tr_b16 v[218:219], v244 offset:7168
	ds_read_b64_tr_b16 v[220:221], v244 offset:5632
	ds_read_b64_tr_b16 v[222:223], v244 offset:7680
	v_mfma_f32_32x32x16_bf16 v[48:63], v[112:115], v[228:231], v[48:63]
	v_max3_f32 v246, v246, v86, v87
	v_max3_f32 v246, v246, v88, v89
	v_max3_f32 v246, v246, v90, v91
	v_max3_f32 v246, v246, v92, v93
	v_max3_f32 v246, v246, v94, v95
	v_mfma_f32_32x32x16_bf16 v[0:15], v[112:115], v[232:235], v[0:15]
	v_max3_f32 v246, v246, v64, v65
	v_max3_f32 v246, v246, v66, v67
	v_max3_f32 v246, v246, v68, v69
	v_max3_f32 v246, v246, v70, v71
	v_max3_f32 v246, v246, v72, v73
	v_mfma_f32_32x32x16_bf16 v[16:31], v[112:115], v[236:239], v[16:31]
	v_max3_f32 v246, v246, v74, v75
	v_max3_f32 v246, v246, v76, v77
	v_max3_f32 v246, v246, v78, v79
	v_mov_b32_e32 v247, v246
	s_nop 1
	v_permlane32_swap_b32_e32 v246, v247
	s_waitcnt lgkmcnt(0)
	v_mfma_f32_32x32x16_bf16 v[32:47], v[116:119], v[200:203], v[32:47]
	v_max_f32_e32 v247, v247, v247
	v_max_f32_e32 v246, v246, v246
	v_max_f32_e32 v246, v246, v247
	v_sub_f32_e32 v247, v246, v204
	v_cmp_ge_f32_e32 vcc, s0, v247
	ds_read_b64_tr_b16 v[224:225], v244 offset:8192
	ds_read_b64_tr_b16 v[226:227], v244 offset:10240
	ds_read_b64_tr_b16 v[228:229], v244 offset:8704
	ds_read_b64_tr_b16 v[230:231], v244 offset:10752
	ds_read_b64_tr_b16 v[232:233], v244 offset:9216
	ds_read_b64_tr_b16 v[234:235], v244 offset:11264
	ds_read_b64_tr_b16 v[236:237], v244 offset:9728
	ds_read_b64_tr_b16 v[238:239], v244 offset:11776
	v_mfma_f32_32x32x16_bf16 v[48:63], v[116:119], v[212:215], v[48:63]
	v_max_f32_e32 v247, v204, v204
	v_max_f32_e32 v248, v247, v246
	v_sub_f32_e32 v246, v204, v248
	v_mul_f32_e32 v246, 0x3dd53b94, v246
	v_exp_f32_e32 v246, v246
	v_mfma_f32_32x32x16_bf16 v[0:15], v[116:119], v[216:219], v[0:15]
	s_cmp_eq_u64 vcc, exec
	s_cselect_b64 s[12:13], -1, 0
	v_cndmask_b32_e64 v205, v246, 1.0, s[12:13]
	v_cndmask_b32_e64 v204, v248, v204, s[12:13]
	v_mul_f32_e32 v246, 0xbdd53b94, v204
	v_mov_b32_e32 v247, v246
	v_fmamk_f32 v80, v80, 0x3dd53b94, v246
	v_mfma_f32_32x32x16_bf16 v[16:31], v[116:119], v[220:223], v[16:31]
	v_fmamk_f32 v81, v81, 0x3dd53b94, v246
	v_fmamk_f32 v82, v82, 0x3dd53b94, v246
	v_fmamk_f32 v83, v83, 0x3dd53b94, v246
	v_fmamk_f32 v84, v84, 0x3dd53b94, v246
	v_fmamk_f32 v85, v85, 0x3dd53b94, v246
	s_waitcnt lgkmcnt(0)
	v_mfma_f32_32x32x16_bf16 v[32:47], v[96:99], v[224:227], v[32:47]
	v_fmamk_f32 v86, v86, 0x3dd53b94, v246
	v_fmamk_f32 v87, v87, 0x3dd53b94, v246
	v_fmamk_f32 v88, v88, 0x3dd53b94, v246
	v_fmamk_f32 v89, v89, 0x3dd53b94, v246
	v_fmamk_f32 v90, v90, 0x3dd53b94, v246
	ds_read_b64_tr_b16 v[200:201], v244 offset:12288
	ds_read_b64_tr_b16 v[202:203], v244 offset:14336
	ds_read_b64_tr_b16 v[212:213], v244 offset:12800
	ds_read_b64_tr_b16 v[214:215], v244 offset:14848
	ds_read_b64_tr_b16 v[216:217], v244 offset:13312
	ds_read_b64_tr_b16 v[218:219], v244 offset:15360
	ds_read_b64_tr_b16 v[220:221], v244 offset:13824
	ds_read_b64_tr_b16 v[222:223], v244 offset:15872
	v_mfma_f32_32x32x16_bf16 v[48:63], v[96:99], v[228:231], v[48:63]
	v_fmamk_f32 v91, v91, 0x3dd53b94, v246
	v_fmamk_f32 v92, v92, 0x3dd53b94, v246
	v_fmamk_f32 v93, v93, 0x3dd53b94, v246
	v_fmamk_f32 v94, v94, 0x3dd53b94, v246
	v_fmac_f32_e32 v247, 0x3dd53b94, v95
	v_mfma_f32_32x32x16_bf16 v[0:15], v[96:99], v[232:235], v[0:15]
	v_exp_f32_e32 v80, v80
	v_exp_f32_e32 v81, v81
	v_exp_f32_e32 v82, v82
	v_exp_f32_e32 v83, v83
	v_exp_f32_e32 v84, v84
	v_mfma_f32_32x32x16_bf16 v[16:31], v[96:99], v[236:239], v[16:31]
	v_exp_f32_e32 v85, v85
	v_exp_f32_e32 v86, v86
	v_exp_f32_e32 v87, v87
	v_exp_f32_e32 v88, v88
	v_exp_f32_e32 v89, v89
	s_waitcnt lgkmcnt(0)
	v_mfma_f32_32x32x16_bf16 v[32:47], v[100:103], v[200:203], v[32:47]
	v_exp_f32_e32 v90, v90
	v_exp_f32_e32 v91, v91
	v_exp_f32_e32 v92, v92
	v_exp_f32_e32 v93, v93
	v_exp_f32_e32 v94, v94
	v_mfma_f32_32x32x16_bf16 v[48:63], v[100:103], v[212:215], v[48:63]
	v_exp_f32_e32 v95, v247
	v_pk_fma_f32 v[78:79], v[78:79], s[68:69], v[246:247] op_sel_hi:[1,0,0]
	v_pk_fma_f32 v[76:77], v[76:77], s[68:69], v[246:247] op_sel_hi:[1,0,0]
	v_pk_fma_f32 v[74:75], v[74:75], s[68:69], v[246:247] op_sel_hi:[1,0,0]
	v_pk_fma_f32 v[72:73], v[72:73], s[68:69], v[246:247] op_sel_hi:[1,0,0]
	v_mfma_f32_32x32x16_bf16 v[0:15], v[100:103], v[216:219], v[0:15]
	v_pk_fma_f32 v[70:71], v[70:71], s[68:69], v[246:247] op_sel_hi:[1,0,0]
	v_pk_fma_f32 v[68:69], v[68:69], s[68:69], v[246:247] op_sel_hi:[1,0,0]
	v_pk_fma_f32 v[66:67], v[66:67], s[68:69], v[246:247] op_sel_hi:[1,0,0]
	v_pk_fma_f32 v[64:65], v[64:65], s[68:69], v[246:247] op_sel_hi:[1,0,0]
	v_mfma_f32_32x32x16_bf16 v[16:31], v[100:103], v[220:223], v[16:31]
	s_mov_b64 s[10:11], 0
	v_cmp_gt_f32_e32 vcc, 1.0, v205
	s_cbranch_vccz .LBB0_752
	s_nop 7
	s_nop 4
	s_and_saveexec_b64 s[16:17], s[8:9]
	ds_write_b32 v195, v205 offset:128
	s_or_b64 exec, exec, s[16:17]
	s_waitcnt lgkmcnt(0)
	v_add_u32_e32 v213, s48, v176
	ds_read_b128 v[200:203], v213 offset:224
	ds_read_b128 v[214:217], v213 offset:192
	ds_read_b128 v[218:221], v213 offset:160
	ds_read_b128 v[222:225], v213 offset:128
	s_waitcnt lgkmcnt(3)
	v_pk_mul_f32 v[44:45], v[44:45], v[200:201]
	s_waitcnt lgkmcnt(2)
	v_pk_mul_f32 v[40:41], v[40:41], v[214:215]
	s_waitcnt lgkmcnt(1)
	v_pk_mul_f32 v[36:37], v[36:37], v[218:219]
	v_pk_mul_f32 v[46:47], v[46:47], v[202:203]
	v_pk_mul_f32 v[42:43], v[42:43], v[216:217]
	v_pk_mul_f32 v[38:39], v[38:39], v[220:221]
	s_waitcnt lgkmcnt(0)
	v_pk_mul_f32 v[34:35], v[34:35], v[224:225]
	v_pk_mul_f32 v[32:33], v[32:33], v[222:223]
	v_pk_mul_f32 v[60:61], v[60:61], v[200:201]
	v_pk_mul_f32 v[56:57], v[56:57], v[214:215]
	v_pk_mul_f32 v[52:53], v[52:53], v[218:219]
	v_pk_mul_f32 v[62:63], v[62:63], v[202:203]
	v_pk_mul_f32 v[58:59], v[58:59], v[216:217]
	v_pk_mul_f32 v[54:55], v[54:55], v[220:221]
	v_pk_mul_f32 v[50:51], v[50:51], v[224:225]
	v_pk_mul_f32 v[48:49], v[48:49], v[222:223]
	v_pk_mul_f32 v[12:13], v[12:13], v[200:201]
	v_pk_mul_f32 v[8:9], v[8:9], v[214:215]
	v_pk_mul_f32 v[4:5], v[4:5], v[218:219]
	v_pk_mul_f32 v[14:15], v[14:15], v[202:203]
	v_pk_mul_f32 v[10:11], v[10:11], v[216:217]
	v_pk_mul_f32 v[6:7], v[6:7], v[220:221]
	v_pk_mul_f32 v[2:3], v[2:3], v[224:225]
	v_pk_mul_f32 v[0:1], v[0:1], v[222:223]
	v_pk_mul_f32 v[28:29], v[28:29], v[200:201]
	v_pk_mul_f32 v[24:25], v[24:25], v[214:215]
	v_pk_mul_f32 v[20:21], v[20:21], v[218:219]
	v_pk_mul_f32 v[30:31], v[30:31], v[202:203]
	v_pk_mul_f32 v[26:27], v[26:27], v[216:217]
	v_pk_mul_f32 v[22:23], v[22:23], v[220:221]
	v_pk_mul_f32 v[18:19], v[18:19], v[224:225]
	v_pk_mul_f32 v[16:17], v[16:17], v[222:223]
	s_branch .LBB0_752

.LBB0_754:
	s_add_u32 s16, s29, 0x1420c000
	s_addc_u32 s17, s30, 0
	s_lshl_b32 s24, s26, 14
	s_add_i32 s28, s24, s51
	v_lshl_add_u64 v[200:201], v[186:187], 1, s[16:17]
	s_mov_b32 s29, m0
	s_mov_b32 m0, s28
	s_nop 0
	global_load_lds_dwordx4 v[200:201], off
	s_mov_b32 m0, s29
	s_addk_i32 s28, 0x2000
	s_cmp_lt_i32 s27, s52
	v_lshl_add_u64 v[200:201], v[188:189], 1, s[16:17]
	s_cselect_b64 s[16:17], -1, 0
	s_cmp_ge_i32 s27, s52
	s_mov_b32 s27, m0
	s_mov_b32 m0, s28
	s_nop 0
	global_load_lds_dwordx4 v[200:201], off
	s_mov_b32 m0, s27
	s_cbranch_scc1 .LBB0_766
	s_mul_i32 s27, s4, 0x6000
	v_add_u32_e32 v232, s27, v206
	v_add_u32_e32 v233, s27, v207
	v_add_u32_e32 v234, s27, v208
	v_add_u32_e32 v235, s27, v209
	ds_read_b128 v[96:99], v232 offset:0
	ds_read_b128 v[100:103], v232 offset:12288
	ds_read_b128 v[200:203], v233 offset:0
	ds_read_b128 v[212:215], v233 offset:12288
	ds_read_b128 v[216:219], v234 offset:0
	ds_read_b128 v[220:223], v234 offset:12288
	ds_read_b128 v[224:227], v235 offset:0
	ds_read_b128 v[228:231], v235 offset:12288
	ds_read_b128 v[244:247], v232 offset:128
	ds_read_b128 v[248:251], v232 offset:12416
	s_waitcnt lgkmcnt(8)
	v_mfma_f32_32x32x16_bf16 v[112:127], v[96:99], v[172:175], 0
	v_add_f32_e32 v241, 0, v80
	v_add_f32_e32 v241, v81, v241
	v_add_f32_e32 v241, v82, v241
	v_add_f32_e32 v241, v83, v241
	v_mfma_f32_32x32x16_bf16 v[96:111], v[100:103], v[172:175], 0
	v_add_f32_e32 v241, v84, v241
	v_add_f32_e32 v241, v85, v241
	v_add_f32_e32 v241, v86, v241
	v_add_f32_e32 v241, v87, v241
	s_waitcnt lgkmcnt(6)
	v_mfma_f32_32x32x16_bf16 v[112:127], v[200:203], v[168:171], v[112:127]
	v_add_f32_e32 v241, v88, v241
	v_add_f32_e32 v241, v89, v241
	v_add_f32_e32 v241, v90, v241
	v_add_f32_e32 v241, v91, v241
	ds_read_b128 v[200:203], v233 offset:128
	v_mfma_f32_32x32x16_bf16 v[96:111], v[212:215], v[168:171], v[96:111]
	v_exp_f32_e32 v64, v64
	v_add_f32_e32 v241, v92, v241
	v_exp_f32_e32 v65, v65
	v_add_f32_e32 v241, v93, v241
	ds_read_b128 v[212:215], v233 offset:12416
	s_waitcnt lgkmcnt(6)
	v_mfma_f32_32x32x16_bf16 v[112:127], v[216:219], v[164:167], v[112:127]
	v_exp_f32_e32 v66, v66
	v_add_f32_e32 v241, v94, v241
	v_exp_f32_e32 v67, v67
	v_add_f32_e32 v241, v95, v241
	ds_read_b128 v[216:219], v234 offset:128
	v_mfma_f32_32x32x16_bf16 v[96:111], v[220:223], v[164:167], v[96:111]
	v_exp_f32_e32 v68, v68
	v_add_f32_e32 v241, v64, v241
	v_exp_f32_e32 v69, v69
	v_add_f32_e32 v241, v65, v241
	ds_read_b128 v[220:223], v234 offset:12416
	s_waitcnt lgkmcnt(6)
	v_mfma_f32_32x32x16_bf16 v[112:127], v[224:227], v[160:163], v[112:127]
	v_exp_f32_e32 v70, v70
	v_add_f32_e32 v241, v66, v241
	v_exp_f32_e32 v71, v71
	v_add_f32_e32 v241, v67, v241
	ds_read_b128 v[224:227], v235 offset:128
	v_mfma_f32_32x32x16_bf16 v[96:111], v[228:231], v[160:163], v[96:111]
	v_exp_f32_e32 v72, v72
	v_add_f32_e32 v241, v68, v241
	v_exp_f32_e32 v73, v73
	v_add_f32_e32 v241, v69, v241
	ds_read_b128 v[228:231], v235 offset:12416
	s_waitcnt lgkmcnt(6)
	v_mfma_f32_32x32x16_bf16 v[112:127], v[244:247], v[156:159], v[112:127]
	v_exp_f32_e32 v74, v74
	v_add_f32_e32 v241, v70, v241
	v_exp_f32_e32 v75, v75
	ds_read_b128 v[244:247], v232 offset:256
	v_mfma_f32_32x32x16_bf16 v[96:111], v[248:251], v[156:159], v[96:111]
	v_add_f32_e32 v241, v71, v241
	v_exp_f32_e32 v76, v76
	v_add_f32_e32 v241, v72, v241
	ds_read_b128 v[248:251], v232 offset:12544
	s_waitcnt lgkmcnt(6)
	v_mfma_f32_32x32x16_bf16 v[112:127], v[200:203], v[152:155], v[112:127]
	v_exp_f32_e32 v77, v77
	v_add_f32_e32 v241, v73, v241
	v_exp_f32_e32 v78, v78
	ds_read_b128 v[200:203], v233 offset:256
	v_mfma_f32_32x32x16_bf16 v[96:111], v[212:215], v[152:155], v[96:111]
	v_add_f32_e32 v241, v74, v241
	v_exp_f32_e32 v79, v79
	v_add_f32_e32 v241, v75, v241
	ds_read_b128 v[212:215], v233 offset:12544
	s_waitcnt lgkmcnt(6)
	v_mfma_f32_32x32x16_bf16 v[112:127], v[216:219], v[148:151], v[112:127]
	v_add_f32_e32 v241, v76, v241
	v_add_f32_e32 v241, v77, v241
	v_add_f32_e32 v241, v78, v241
	ds_read_b128 v[216:219], v234 offset:256
	v_mfma_f32_32x32x16_bf16 v[96:111], v[220:223], v[148:151], v[96:111]
	v_add_f32_e32 v241, v79, v241
	v_mov_b32_e32 v242, v241
	v_cvt_pk_bf16_f32 v80, v80, v81
	ds_read_b128 v[220:223], v234 offset:12544
	s_waitcnt lgkmcnt(6)
	v_mfma_f32_32x32x16_bf16 v[112:127], v[224:227], v[144:147], v[112:127]
	v_cvt_pk_bf16_f32 v81, v82, v83
	v_permlane32_swap_b32_e32 v241, v242
	v_cvt_pk_bf16_f32 v82, v84, v85
	ds_read_b128 v[224:227], v235 offset:256
	v_mfma_f32_32x32x16_bf16 v[96:111], v[228:231], v[144:147], v[96:111]
	v_cvt_pk_bf16_f32 v83, v86, v87
	v_cvt_pk_bf16_f32 v84, v88, v89
	v_cvt_pk_bf16_f32 v85, v90, v91
	ds_read_b128 v[228:231], v235 offset:12544
	s_waitcnt lgkmcnt(6)
	v_mfma_f32_32x32x16_bf16 v[112:127], v[244:247], v[140:143], v[112:127]
	v_cvt_pk_bf16_f32 v86, v92, v93
	v_cvt_pk_bf16_f32 v87, v94, v95
	v_cvt_pk_bf16_f32 v64, v64, v65
	v_mfma_f32_32x32x16_bf16 v[96:111], v[248:251], v[140:143], v[96:111]
	v_cvt_pk_bf16_f32 v65, v66, v67
	v_cvt_pk_bf16_f32 v66, v68, v69
	v_cvt_pk_bf16_f32 v67, v70, v71
	s_waitcnt lgkmcnt(4)
	v_mfma_f32_32x32x16_bf16 v[112:127], v[200:203], v[136:139], v[112:127]
	v_cvt_pk_bf16_f32 v68, v72, v73
	v_cvt_pk_bf16_f32 v69, v74, v75
	v_cvt_pk_bf16_f32 v70, v76, v77
	v_mfma_f32_32x32x16_bf16 v[96:111], v[212:215], v[136:139], v[96:111]
	v_cvt_pk_bf16_f32 v71, v78, v79
	v_add_f32_e32 v243, v241, v242
	v_fmac_f32_e32 v243, v205, v211
	s_waitcnt lgkmcnt(2)
	v_mfma_f32_32x32x16_bf16 v[112:127], v[216:219], v[132:135], v[112:127]
	v_permlane32_swap_b32_e32 v80, v82
	v_permlane32_swap_b32_e32 v81, v83
	v_permlane32_swap_b32_e32 v84, v86
	v_mfma_f32_32x32x16_bf16 v[96:111], v[220:223], v[132:135], v[96:111]
	v_permlane32_swap_b32_e32 v85, v87
	v_permlane32_swap_b32_e32 v64, v66
	v_permlane32_swap_b32_e32 v65, v67
	s_waitcnt lgkmcnt(0)
	v_mfma_f32_32x32x16_bf16 v[112:127], v[224:227], v[128:131], v[112:127]
	v_permlane32_swap_b32_e32 v68, v70
	v_permlane32_swap_b32_e32 v69, v71
	v_mov_b32_e32 v211, v243
	v_mfma_f32_32x32x16_bf16 v[96:111], v[228:231], v[128:131], v[96:111]
	v_lshl_add_u32 v244, s62, 14, v196
	ds_read_b64_tr_b16 v[224:225], v244 offset:0
	ds_read_b64_tr_b16 v[226:227], v244 offset:2048
	ds_read_b64_tr_b16 v[228:229], v244 offset:512
	ds_read_b64_tr_b16 v[230:231], v244 offset:2560
	ds_read_b64_tr_b16 v[232:233], v244 offset:1024
	ds_read_b64_tr_b16 v[234:235], v244 offset:3072
	ds_read_b64_tr_b16 v[236:237], v244 offset:1536
	ds_read_b64_tr_b16 v[238:239], v244 offset:3584
	s_waitcnt lgkmcnt(0)
	v_mfma_f32_32x32x16_bf16 v[32:47], v[80:83], v[224:227], v[32:47]
	v_max_f32_e32 v246, v113, v113
	v_max_f32_e32 v247, v112, v112
	v_max_f32_e32 v246, v247, v246
	v_max3_f32 v246, v246, v114, v115
	v_max3_f32 v246, v246, v116, v117
	ds_read_b64_tr_b16 v[200:201], v244 offset:4096
	ds_read_b64_tr_b16 v[202:203], v244 offset:6144
	ds_read_b64_tr_b16 v[212:213], v244 offset:4608
	ds_read_b64_tr_b16 v[214:215], v244 offset:6656
	ds_read_b64_tr_b16 v[216:217], v244 offset:5120
	ds_read_b64_tr_b16 v[218:219], v244 offset:7168
	ds_read_b64_tr_b16 v[220:221], v244 offset:5632
	ds_read_b64_tr_b16 v[222:223], v244 offset:7680
	v_mfma_f32_32x32x16_bf16 v[48:63], v[80:83], v[228:231], v[48:63]
	v_max3_f32 v246, v246, v118, v119
	v_max3_f32 v246, v246, v120, v121
	v_max3_f32 v246, v246, v122, v123
	v_max3_f32 v246, v246, v124, v125
	v_max3_f32 v246, v246, v126, v127
	v_mfma_f32_32x32x16_bf16 v[0:15], v[80:83], v[232:235], v[0:15]
	v_max3_f32 v246, v246, v96, v97
	v_max3_f32 v246, v246, v98, v99
	v_max3_f32 v246, v246, v100, v101
	v_max3_f32 v246, v246, v102, v103
	v_max3_f32 v246, v246, v104, v105
	v_mfma_f32_32x32x16_bf16 v[16:31], v[80:83], v[236:239], v[16:31]
	v_max3_f32 v246, v246, v106, v107
	v_max3_f32 v246, v246, v108, v109
	v_max3_f32 v246, v246, v110, v111
	v_mov_b32_e32 v247, v246
	s_nop 1
	v_permlane32_swap_b32_e32 v246, v247
	s_waitcnt lgkmcnt(0)
	v_mfma_f32_32x32x16_bf16 v[32:47], v[84:87], v[200:203], v[32:47]
	v_max_f32_e32 v247, v247, v247
	v_max_f32_e32 v246, v246, v246
	v_max_f32_e32 v246, v246, v247
	v_sub_f32_e32 v247, v246, v204
	v_cmp_ge_f32_e32 vcc, s0, v247
	ds_read_b64_tr_b16 v[224:225], v244 offset:8192
	ds_read_b64_tr_b16 v[226:227], v244 offset:10240
	ds_read_b64_tr_b16 v[228:229], v244 offset:8704
	ds_read_b64_tr_b16 v[230:231], v244 offset:10752
	ds_read_b64_tr_b16 v[232:233], v244 offset:9216
	ds_read_b64_tr_b16 v[234:235], v244 offset:11264
	ds_read_b64_tr_b16 v[236:237], v244 offset:9728
	ds_read_b64_tr_b16 v[238:239], v244 offset:11776
	v_mfma_f32_32x32x16_bf16 v[48:63], v[84:87], v[212:215], v[48:63]
	v_max_f32_e32 v247, v204, v204
	v_max_f32_e32 v248, v247, v246
	v_sub_f32_e32 v246, v204, v248
	v_mul_f32_e32 v246, 0x3dd53b94, v246
	v_exp_f32_e32 v246, v246
	v_mfma_f32_32x32x16_bf16 v[0:15], v[84:87], v[216:219], v[0:15]
	s_cmp_eq_u64 vcc, exec
	s_cselect_b64 s[10:11], -1, 0
	v_cndmask_b32_e64 v210, v246, 1.0, s[10:11]
	v_cndmask_b32_e64 v204, v248, v204, s[10:11]
	v_mul_f32_e32 v246, 0xbdd53b94, v204
	v_mov_b32_e32 v247, v246
	v_fmamk_f32 v112, v112, 0x3dd53b94, v246
	v_mfma_f32_32x32x16_bf16 v[16:31], v[84:87], v[220:223], v[16:31]
	v_fmamk_f32 v113, v113, 0x3dd53b94, v246
	v_fmamk_f32 v114, v114, 0x3dd53b94, v246
	v_fmamk_f32 v115, v115, 0x3dd53b94, v246
	v_fmamk_f32 v116, v116, 0x3dd53b94, v246
	v_fmamk_f32 v117, v117, 0x3dd53b94, v246
	s_waitcnt lgkmcnt(0)
	v_mfma_f32_32x32x16_bf16 v[32:47], v[64:67], v[224:227], v[32:47]
	v_fmamk_f32 v118, v118, 0x3dd53b94, v246
	v_fmamk_f32 v119, v119, 0x3dd53b94, v246
	v_fmamk_f32 v120, v120, 0x3dd53b94, v246
	v_fmamk_f32 v121, v121, 0x3dd53b94, v246
	v_fmamk_f32 v122, v122, 0x3dd53b94, v246
	ds_read_b64_tr_b16 v[200:201], v244 offset:12288
	ds_read_b64_tr_b16 v[202:203], v244 offset:14336
	ds_read_b64_tr_b16 v[212:213], v244 offset:12800
	ds_read_b64_tr_b16 v[214:215], v244 offset:14848
	ds_read_b64_tr_b16 v[216:217], v244 offset:13312
	ds_read_b64_tr_b16 v[218:219], v244 offset:15360
	ds_read_b64_tr_b16 v[220:221], v244 offset:13824
	ds_read_b64_tr_b16 v[222:223], v244 offset:15872
	v_mfma_f32_32x32x16_bf16 v[48:63], v[64:67], v[228:231], v[48:63]
	v_fmamk_f32 v123, v123, 0x3dd53b94, v246
	v_fmamk_f32 v124, v124, 0x3dd53b94, v246
	v_fmamk_f32 v125, v125, 0x3dd53b94, v246
	v_fmamk_f32 v126, v126, 0x3dd53b94, v246
	v_fmac_f32_e32 v247, 0x3dd53b94, v127
	v_mfma_f32_32x32x16_bf16 v[0:15], v[64:67], v[232:235], v[0:15]
	v_exp_f32_e32 v112, v112
	v_exp_f32_e32 v113, v113
	v_exp_f32_e32 v114, v114
	v_exp_f32_e32 v115, v115
	v_exp_f32_e32 v116, v116
	v_mfma_f32_32x32x16_bf16 v[16:31], v[64:67], v[236:239], v[16:31]
	v_exp_f32_e32 v117, v117
	v_exp_f32_e32 v118, v118
	v_exp_f32_e32 v119, v119
	v_exp_f32_e32 v120, v120
	v_exp_f32_e32 v121, v121
	s_waitcnt lgkmcnt(0)
	v_mfma_f32_32x32x16_bf16 v[32:47], v[68:71], v[200:203], v[32:47]
	v_exp_f32_e32 v122, v122
	v_exp_f32_e32 v123, v123
	v_exp_f32_e32 v124, v124
	v_exp_f32_e32 v125, v125
	v_exp_f32_e32 v126, v126
	v_mfma_f32_32x32x16_bf16 v[48:63], v[68:71], v[212:215], v[48:63]
	v_exp_f32_e32 v127, v247
	v_pk_fma_f32 v[110:111], v[110:111], s[68:69], v[246:247] op_sel_hi:[1,0,0]
	v_pk_fma_f32 v[108:109], v[108:109], s[68:69], v[246:247] op_sel_hi:[1,0,0]
	v_pk_fma_f32 v[106:107], v[106:107], s[68:69], v[246:247] op_sel_hi:[1,0,0]
	v_pk_fma_f32 v[104:105], v[104:105], s[68:69], v[246:247] op_sel_hi:[1,0,0]
	v_mfma_f32_32x32x16_bf16 v[0:15], v[68:71], v[216:219], v[0:15]
	v_pk_fma_f32 v[102:103], v[102:103], s[68:69], v[246:247] op_sel_hi:[1,0,0]
	v_pk_fma_f32 v[100:101], v[100:101], s[68:69], v[246:247] op_sel_hi:[1,0,0]
	v_pk_fma_f32 v[98:99], v[98:99], s[68:69], v[246:247] op_sel_hi:[1,0,0]
	v_pk_fma_f32 v[96:97], v[96:97], s[68:69], v[246:247] op_sel_hi:[1,0,0]
	v_mfma_f32_32x32x16_bf16 v[16:31], v[68:71], v[220:223], v[16:31]
	v_cmp_gt_f32_e32 vcc, 1.0, v210
	s_cbranch_vccz .Lh2_tail
	s_nop 7
	s_nop 4
	s_and_saveexec_b64 s[16:17], s[8:9]
	ds_write_b32 v195, v210 offset:128
	s_or_b64 exec, exec, s[16:17]
	s_waitcnt lgkmcnt(0)
	v_add_u32_e32 v213, s48, v176
	ds_read_b128 v[200:203], v213 offset:224
	ds_read_b128 v[214:217], v213 offset:192
	ds_read_b128 v[218:221], v213 offset:160
	ds_read_b128 v[222:225], v213 offset:128
	s_waitcnt lgkmcnt(3)
	v_pk_mul_f32 v[44:45], v[44:45], v[200:201]
	s_waitcnt lgkmcnt(2)
	v_pk_mul_f32 v[40:41], v[40:41], v[214:215]
	s_waitcnt lgkmcnt(1)
	v_pk_mul_f32 v[36:37], v[36:37], v[218:219]
	v_pk_mul_f32 v[46:47], v[46:47], v[202:203]
	v_pk_mul_f32 v[42:43], v[42:43], v[216:217]
	v_pk_mul_f32 v[38:39], v[38:39], v[220:221]
	s_waitcnt lgkmcnt(0)
	v_pk_mul_f32 v[34:35], v[34:35], v[224:225]
	v_pk_mul_f32 v[32:33], v[32:33], v[222:223]
	v_pk_mul_f32 v[60:61], v[60:61], v[200:201]
	v_pk_mul_f32 v[56:57], v[56:57], v[214:215]
	v_pk_mul_f32 v[52:53], v[52:53], v[218:219]
	v_pk_mul_f32 v[62:63], v[62:63], v[202:203]
	v_pk_mul_f32 v[58:59], v[58:59], v[216:217]
	v_pk_mul_f32 v[54:55], v[54:55], v[220:221]
	v_pk_mul_f32 v[50:51], v[50:51], v[224:225]
	v_pk_mul_f32 v[48:49], v[48:49], v[222:223]
	v_pk_mul_f32 v[12:13], v[12:13], v[200:201]
	v_pk_mul_f32 v[8:9], v[8:9], v[214:215]
	v_pk_mul_f32 v[4:5], v[4:5], v[218:219]
	v_pk_mul_f32 v[14:15], v[14:15], v[202:203]
	v_pk_mul_f32 v[10:11], v[10:11], v[216:217]
	v_pk_mul_f32 v[6:7], v[6:7], v[220:221]
	v_pk_mul_f32 v[2:3], v[2:3], v[224:225]
	v_pk_mul_f32 v[0:1], v[0:1], v[222:223]
	v_pk_mul_f32 v[28:29], v[28:29], v[200:201]
	v_pk_mul_f32 v[24:25], v[24:25], v[214:215]
	v_pk_mul_f32 v[20:21], v[20:21], v[218:219]
	v_pk_mul_f32 v[30:31], v[30:31], v[202:203]
	v_pk_mul_f32 v[26:27], v[26:27], v[216:217]
	v_pk_mul_f32 v[22:23], v[22:23], v[220:221]
	v_pk_mul_f32 v[18:19], v[18:19], v[224:225]
	v_pk_mul_f32 v[16:17], v[16:17], v[222:223]
	s_branch .Lh2_tail
